# split-phase grid barrier 2: weight-conversion workgroups convert w_out / c_ws before waiting for it (the w_in[1]^T overwrite comes after the wait); prep workgroups wait at once; hand-written arrive wi
# speedup vs baseline: 1.0097x; 1.0097x over previous
.LBB0_311:
	s_waitcnt vmcnt(0)
	v_readlane_b32 s0, v255, 1
	v_readlane_b32 s1, v255, 2
	s_waitcnt lgkmcnt(0)
	s_barrier
	s_and_saveexec_b64 s[4:5], s[0:1]
	s_cbranch_execz .LBB0_363
	s_mov_b64 s[98:99], s[94:95]
	s_lshl_b32 s0, s3, 8
	s_add_u32 s100, s98, s0
	s_addc_u32 s101, s99, 0
	v_mov_b32_e32 v19, 0x10000
	s_waitcnt vmcnt(0) expcnt(0) lgkmcnt(0)
	ds_read_b32 v2, v19
	v_mov_b32_e32 v19, 0x10004
	ds_read_b32 v5, v19
	v_mov_b32_e32 v3, 0x1000
	v_mov_b32_e32 v4, 1
	global_atomic_add v3, v3, v4, s[100:101] offset:1024 sc0
	s_waitcnt vmcnt(0) lgkmcnt(0)
	v_add_u32_e32 v3, 1, v3
	v_mul_u32_u24_e32 v6, 2, v2
	v_add_u32_e32 v6, 1, v6
	v_cmp_eq_u32_e32 vcc, v3, v6
	s_cbranch_vccz .Lgb2_nf
	buffer_wbl2 sc1
.Lgb2_nf:
	v_mul_u32_u24_e32 v6, 3, v2
	v_cmp_eq_u32_e32 vcc, v3, v6
	s_cbranch_vccz .Lgb2_wait
	buffer_wbl2 sc1
	s_waitcnt vmcnt(0)
	v_mov_b32_e32 v3, 0x3000
	global_atomic_add v3, v3, v4, s[98:99] offset:1024 sc0
	v_readlane_b32 s0, v255, 11
	s_nop 3
	s_sub_i32 s0, 3, s0
	s_nop 0
	v_mul_lo_u32 v6, v5, s0
	s_waitcnt vmcnt(0)
	v_add_u32_e32 v3, 1, v3
	v_cmp_eq_u32_e32 vcc, v3, v6
	s_cbranch_vccz .Lgb2_wait
	v_mov_b32_e32 v3, 0x3500
	global_atomic_add v3, v4, s[98:99]
	v_mov_b32_e32 v3, 0x2400
	global_atomic_add v3, v4, s[98:99]
	v_add_u32_e32 v3, 0x100, v3
	global_atomic_add v3, v4, s[98:99]
	v_add_u32_e32 v3, 0x100, v3
	global_atomic_add v3, v4, s[98:99]
	v_add_u32_e32 v3, 0x100, v3
	global_atomic_add v3, v4, s[98:99]
	v_add_u32_e32 v3, 0x100, v3
	global_atomic_add v3, v4, s[98:99]
	v_add_u32_e32 v3, 0x100, v3
	global_atomic_add v3, v4, s[98:99]
	v_add_u32_e32 v3, 0x100, v3
	global_atomic_add v3, v4, s[98:99]
	v_add_u32_e32 v3, 0x100, v3
	global_atomic_add v3, v4, s[98:99]
	v_add_u32_e32 v3, 0x100, v3
	global_atomic_add v3, v4, s[98:99]
	v_add_u32_e32 v3, 0x100, v3
	global_atomic_add v3, v4, s[98:99]
	v_add_u32_e32 v3, 0x100, v3
	global_atomic_add v3, v4, s[98:99]
	v_add_u32_e32 v3, 0x100, v3
	global_atomic_add v3, v4, s[98:99]
	v_add_u32_e32 v3, 0x100, v3
	global_atomic_add v3, v4, s[98:99]
	v_add_u32_e32 v3, 0x100, v3
	global_atomic_add v3, v4, s[98:99]
	v_add_u32_e32 v3, 0x100, v3
	global_atomic_add v3, v4, s[98:99]
	v_add_u32_e32 v3, 0x100, v3
	global_atomic_add v3, v4, s[98:99]
.Lgb2_wait:
.LBB0_363:
	s_or_b64 exec, exec, s[4:5]
	s_cmpk_gt_i32 s76, 0x63f
	s_waitcnt lgkmcnt(0)
	s_barrier
	s_cbranch_scc1 .LBB0_429
	s_cmpk_gt_i32 s76, 0xff
	s_cbranch_scc1 .Lw2_pre_skip
	s_mov_b64 s[98:99], exec
	v_readlane_b32 s0, v255, 1
	v_readlane_b32 s1, v255, 2
	s_nop 1
	s_mov_b64 exec, s[0:1]
	s_cbranch_execz .Lw2p_skip
	s_mov_b64 s[100:101], s[94:95]
	s_lshl_b32 s0, s3, 8
	s_add_u32 s100, s100, s0
	s_addc_u32 s101, s101, 0
	v_mov_b32_e32 v3, 0x2000
	v_mov_b32_e32 v5, 0
	s_nop 4
.Lw2p_loop:
	global_load_dword v4, v3, s[100:101] offset:1024 sc1
	s_waitcnt vmcnt(0)
	v_cmp_le_u32_e32 vcc, 3, v4
	s_cbranch_vccnz .Lw2p_done
	s_sleep 1
	v_add_u32_e32 v5, 1, v5
	v_cmp_gt_u32_e32 vcc, 0x8000, v5
	s_cbranch_vccnz .Lw2p_loop

.Lw2_pre_skip:
	s_add_i32 s0, s42, 0xffffff00
	s_cmpk_gt_i32 s76, 0xff
	s_cselect_b32 s0, s0, 0x640
	s_cmpk_gt_i32 s42, 0x1ff
	s_cselect_b32 s39, s0, s42
	s_add_u32 s6, s58, 0xa00000
	v_writelane_b32 v255, s94, 5
	s_addc_u32 s7, s59, 0
	s_add_u32 s0, s72, 0x400000
	v_writelane_b32 v255, s95, 6
	v_writelane_b32 v255, s0, 7
	s_addc_u32 s0, s73, 0
	v_writelane_b32 v255, s0, 8
	s_add_u32 s0, s58, 0x800000
	v_writelane_b32 v255, s0, 9
	s_addc_u32 s0, s59, 0
	s_add_u32 s80, s58, 0x600000
	s_addc_u32 s81, s59, 0
	s_add_u32 s70, s70, 0xc00000
	s_addc_u32 s71, s71, 0
	s_add_u32 s8, s58, 0x2cd1000
	s_addc_u32 s9, s59, 0
	s_add_u32 s10, s58, 0xccd1000
	s_addc_u32 s11, s59, 0
	s_add_u32 s82, s58, 0xbcd1000
	s_addc_u32 s83, s59, 0
	s_mov_b32 s84, s56
	s_mov_b32 s85, s57
	s_add_u32 s12, s58, 0xa40000
	s_addc_u32 s13, s59, 0
	s_add_u32 s28, s58, 0xc50000
	s_addc_u32 s29, s59, 0
	s_add_u32 s30, s58, 0xc90000
	s_addc_u32 s31, s59, 0
	s_add_u32 s86, s58, 0xcd0000
	s_addc_u32 s87, s59, 0
	s_add_u32 s88, s58, 0xdcd1000
	s_addc_u32 s89, s59, 0
	v_mbcnt_lo_u32_b32 v0, -1, 0
	s_add_u32 s34, s58, 0xa40060
	v_mbcnt_hi_u32_b32 v234, -1, v0
	v_bfrev_b32_e32 v0, 0.5
	v_writelane_b32 v255, s0, 10
	s_addc_u32 s35, s59, 0
	v_mov_b32_e32 v205, 0
	s_movk_i32 s90, 0x104
	s_movk_i32 s91, 0x3000
	s_movk_i32 s92, 0x1000
	s_movk_i32 s93, 0x1800
	s_movk_i32 s94, 0x2000
	s_movk_i32 s95, 0x4000
	s_mov_b32 s96, 0x9cd1000
	s_mov_b32 s97, 0xacd1000
	s_mov_b32 s33, 0xccd1000
	s_mov_b32 s74, 0xcd1000
	s_mov_b32 s75, 0xbcd1000
	s_movk_i32 s78, 0x200
	v_mov_b32_e32 v254, 0x7f800000
	v_mov_b32_e32 v232, 0x7fc00000
	v_mov_b32_e32 v233, 0xff800000
	v_lshl_or_b32 v235, v234, 2, v0
	s_mov_b32 s2, s76
	s_mov_b32 s77, s76
	s_mov_b32 s98, 0
	s_nop 0
	v_writelane_b32 v255, s98, 15
	s_cmpk_lt_i32 s76, 0x100
	s_cbranch_scc1 .Lp3_init_done
	s_addk_i32 s77, 0x300
	s_addk_i32 s2, 0x300
.Lp3_init_done:
	s_mov_b32 s37, 0
	s_mov_b32 s38, 0x3db504f3
	s_mov_b64 s[40:41], 0x2000
	s_mov_b64 s[62:63], 0xc00
	s_branch .LBB0_367

.LBB0_366:
	s_add_i32 s77, s77, s39
	s_add_i32 s2, s2, s39
	s_cmpk_lt_i32 s76, 0x100
	s_cbranch_scc1 .Lp3_orig_latch
	v_readlane_b32 s0, v255, 15
	s_nop 3
	s_cmp_lg_u32 s0, 0
	s_cbranch_scc1 .Lp3_phase_b
	s_cmpk_lt_i32 s77, 0x640
	s_cbranch_scc1 .LBB0_367
	s_mov_b32 s0, 1
	s_nop 0
	v_writelane_b32 v255, s0, 15
	s_mov_b32 s77, s76
	s_mov_b32 s2, s76
	s_mov_b64 s[98:99], exec
	v_readlane_b32 s0, v255, 1
	v_readlane_b32 s1, v255, 2
	s_nop 1
	s_mov_b64 exec, s[0:1]
	s_cbranch_execz .Lw2t_skip
	v_readlane_b32 s100, v255, 5
	v_readlane_b32 s101, v255, 6
	s_nop 3
	s_lshl_b32 s0, s3, 8
	s_add_u32 s100, s100, s0
	s_addc_u32 s101, s101, 0
	v_mov_b32_e32 v3, 0x2000
	v_mov_b32_e32 v5, 0
	s_nop 4

.Lp3_phase_b:
	s_cmpk_lt_i32 s77, 0x400
	s_cbranch_scc1 .LBB0_367
	s_branch .LBB0_428
.Lp3_orig_latch:
	s_cmpk_lt_i32 s77, 0x640
	s_cbranch_scc0 .LBB0_428
